# nt hint on read-once streaming loads: prologue f32 x loads and final-norm bf16 residual loads
# speedup vs baseline: 1.0047x; 1.0047x over previous
; __device__ __forceinline__ unsigned pk2(float lo, float hi) { return pg8::cvt_pk_bf16(lo, hi); }
; __global__ void __launch_bounds__(NTHREADS, 2) fwd_megakernel(Params p) {
;     ...
;         for (int u = gw; u < 2048; u += NGW) {
;             const int nb = u & 15, k8 = (u >> 4) & 15, g = (u >> 8) & 3, e = u >> 10, n = nb * 64 + lane, k0 = k8 * 8;
;             const float* wp = p.w_pool + ((size_t)(e * 4 + g) * 128 + k0) * 128; const float* sc = p.pool_scale + e * 512 + g * 128;
;             const float* wo = p.w_out_even + ((size_t)e * 1024 + 512 + g * 128) * 1024 + n;
;             float acc[8];
; #pragma unroll
;             for (int i = 0; i < 8; ++i) acc[i] = 0.f;
; #pragma unroll 16
;             for (int jj = 0; jj < 128; ++jj) { const float w = wo[(size_t)jj * 1024] * sc[jj];
; #pragma unroll
;                 for (int i = 0; i < 8; ++i) acc[i] += wp[i * 128 + jj] * w; }
;             u32x4 o; o.x = pk2(acc[0], acc[1]); o.y = pk2(acc[2], acc[3]); o.z = pk2(acc[4], acc[5]); o.w = pk2(acc[6], acc[7]);
;             *(u32x4*)((bf16_t*)(ws + WS_WOUT_E) + (size_t)e * 1024 * 1024 + (size_t)n * 1024 + 512 + g * 128 + k0) = o;
.LBB0_15:
	v_add_co_u32_e64 v30, s[0:1], s43, v4
	v_add_co_u32_e32 v14, vcc, 0xffff1000, v4
	s_nop 0
	v_addc_co_u32_e64 v31, s[0:1], -1, v5, s[0:1]
	v_add_co_u32_e64 v16, s[0:1], s30, v4
	s_add_u32 s24, s47, s22
	s_nop 0
	v_addc_co_u32_e64 v17, s[0:1], -1, v5, s[0:1]
	v_add_co_u32_e64 v18, s[0:1], s31, v4
	v_addc_co_u32_e32 v15, vcc, -1, v5, vcc
	s_nop 0
	v_addc_co_u32_e64 v19, s[0:1], -1, v5, s[0:1]
	v_add_co_u32_e64 v20, s[0:1], s39, v4
	s_addc_u32 s25, s48, s23
	s_nop 0
	v_addc_co_u32_e64 v21, s[0:1], -1, v5, s[0:1]
	v_add_co_u32_e64 v22, s[0:1], s40, v4
	s_nop 1
	v_addc_co_u32_e64 v23, s[0:1], -1, v5, s[0:1]
	v_add_co_u32_e64 v24, s[0:1], s41, v4
	s_nop 1
	v_addc_co_u32_e64 v25, s[0:1], -1, v5, s[0:1]
	v_add_co_u32_e64 v26, s[0:1], s42, v4
	s_nop 1
	v_addc_co_u32_e64 v27, s[0:1], -1, v5, s[0:1]
	global_load_dword v43, v[16:17], off offset:-4096
	global_load_dword v160, v[16:17], off
	global_load_dword v161, v[18:19], off offset:-4096
	global_load_dword v162, v[18:19], off
	global_load_dword v163, v[20:21], off offset:-4096
	global_load_dword v164, v[20:21], off
	global_load_dword v165, v[22:23], off offset:-4096
	global_load_dword v166, v[22:23], off
	global_load_dword v167, v[24:25], off offset:-4096
	global_load_dword v168, v[24:25], off
	global_load_dword v169, v[26:27], off offset:-4096
	global_load_dword v170, v[26:27], off
	global_load_dword v171, v[4:5], off offset:-4096
	global_load_dword v172, v[4:5], off
	global_load_dword v2, v[14:15], off
	s_nop 0
	global_load_dwordx4 v[14:17], v3, s[24:25]
	global_load_dwordx4 v[18:21], v3, s[24:25] offset:16
	global_load_dwordx4 v[22:25], v3, s[24:25] offset:32
	global_load_dwordx4 v[26:29], v3, s[24:25] offset:48
	global_load_dword v173, v[30:31], off
	s_add_u32 s0, s45, s22
	s_addc_u32 s1, s46, s23
	global_load_dwordx4 v[30:33], v3, s[0:1] nt
	global_load_dwordx4 v[34:37], v3, s[0:1] offset:512 nt
	global_load_dwordx4 v[38:41], v3, s[0:1] offset:1024 nt
	global_load_dwordx4 v[44:47], v3, s[0:1] offset:1536 nt
	global_load_dwordx4 v[48:51], v3, s[0:1] offset:2048 nt
	global_load_dwordx4 v[52:55], v3, s[0:1] offset:2560 nt
	global_load_dwordx4 v[56:59], v3, s[0:1] offset:3072 nt
	global_load_dwordx4 v[60:63], v3, s[0:1] offset:3584 nt
	global_load_dwordx4 v[64:67], v3, s[0:1] offset:16 nt
	global_load_dwordx4 v[68:71], v3, s[0:1] offset:528 nt
	global_load_dwordx4 v[72:75], v3, s[0:1] offset:1040 nt
	global_load_dwordx4 v[76:79], v3, s[0:1] offset:1552 nt
	global_load_dwordx4 v[80:83], v3, s[0:1] offset:2064 nt
	global_load_dwordx4 v[84:87], v3, s[0:1] offset:2576 nt
	global_load_dwordx4 v[88:91], v3, s[0:1] offset:3088 nt
	global_load_dwordx4 v[92:95], v3, s[0:1] offset:3600 nt
	global_load_dwordx4 v[96:99], v3, s[0:1] offset:32 nt
	global_load_dwordx4 v[100:103], v3, s[0:1] offset:48 nt
	global_load_dwordx4 v[104:107], v3, s[0:1] offset:544 nt
	global_load_dwordx4 v[108:111], v3, s[0:1] offset:560 nt
	global_load_dwordx4 v[112:115], v3, s[0:1] offset:1056 nt
	global_load_dwordx4 v[116:119], v3, s[0:1] offset:1072 nt
	global_load_dwordx4 v[120:123], v3, s[0:1] offset:1568 nt
	global_load_dwordx4 v[124:127], v3, s[0:1] offset:1584 nt
	global_load_dwordx4 v[128:131], v3, s[0:1] offset:2080 nt
	global_load_dwordx4 v[132:135], v3, s[0:1] offset:2096 nt
	global_load_dwordx4 v[136:139], v3, s[0:1] offset:2592 nt
	global_load_dwordx4 v[140:143], v3, s[0:1] offset:2608 nt
	global_load_dwordx4 v[144:147], v3, s[0:1] offset:3104 nt
	global_load_dwordx4 v[148:151], v3, s[0:1] offset:3120 nt
	global_load_dwordx4 v[152:155], v3, s[0:1] offset:3616 nt
	global_load_dwordx4 v[156:159], v3, s[0:1] offset:3632 nt
	s_add_u32 s22, s22, 64
	s_addc_u32 s23, s23, 0
	v_lshl_add_u64 v[4:5], v[4:5], 0, s[14:15]
	s_cmpk_eq_i32 s22, 0x200
	s_waitcnt vmcnt(31)
	v_mov_b32_e32 v174, v30
	s_waitcnt vmcnt(30)
	v_mov_b32_e32 v175, v34
	v_mov_b32_e32 v34, v31
	v_mov_b32_e32 v30, v32
	v_mov_b32_e32 v31, v36
	v_mov_b32_e32 v36, v33
	s_waitcnt vmcnt(29)
	v_mov_b32_e32 v32, v38
	s_waitcnt vmcnt(28)
	v_mov_b32_e32 v33, v44
	v_mov_b32_e32 v44, v39
	v_mov_b32_e32 v38, v40
	v_mov_b32_e32 v39, v46
	v_mov_b32_e32 v46, v41
	s_waitcnt vmcnt(27)
	v_mov_b32_e32 v40, v48
	s_waitcnt vmcnt(26)
	v_mov_b32_e32 v41, v52
	v_mov_b32_e32 v52, v49
	v_mov_b32_e32 v48, v50
	v_mov_b32_e32 v49, v54
	v_mov_b32_e32 v54, v51
	s_waitcnt vmcnt(25)
	v_mov_b32_e32 v50, v56
	s_waitcnt vmcnt(24)
	v_mov_b32_e32 v51, v60
	v_mov_b32_e32 v60, v57
	v_mov_b32_e32 v56, v58
	v_mov_b32_e32 v57, v62
	v_mov_b32_e32 v62, v59
	v_mul_f32_e32 v2, v2, v14
	v_mul_f32_e32 v14, v43, v15
	v_pk_fma_f32 v[12:13], v[2:3], v[174:175], v[12:13] op_sel_hi:[0,1,1]
	v_pk_fma_f32 v[10:11], v[2:3], v[32:33], v[10:11] op_sel_hi:[0,1,1]
	v_pk_fma_f32 v[8:9], v[2:3], v[40:41], v[8:9] op_sel_hi:[0,1,1]
	v_pk_fma_f32 v[6:7], v[2:3], v[50:51], v[6:7] op_sel_hi:[0,1,1]
	v_mul_f32_e32 v16, v160, v16
	v_pk_fma_f32 v[12:13], v[14:15], v[34:35], v[12:13] op_sel_hi:[0,1,1]
	v_pk_fma_f32 v[10:11], v[14:15], v[44:45], v[10:11] op_sel_hi:[0,1,1]
	v_pk_fma_f32 v[8:9], v[14:15], v[52:53], v[8:9] op_sel_hi:[0,1,1]
	v_pk_fma_f32 v[6:7], v[14:15], v[60:61], v[6:7] op_sel_hi:[0,1,1]
	v_mul_f32_e32 v160, v161, v17
	v_pk_fma_f32 v[12:13], v[16:17], v[30:31], v[12:13] op_sel_hi:[0,1,1]
	v_pk_fma_f32 v[10:11], v[16:17], v[38:39], v[10:11] op_sel_hi:[0,1,1]
	v_pk_fma_f32 v[8:9], v[16:17], v[48:49], v[8:9] op_sel_hi:[0,1,1]
	v_pk_fma_f32 v[6:7], v[16:17], v[56:57], v[6:7] op_sel_hi:[0,1,1]
	v_mul_f32_e32 v18, v162, v18
	s_waitcnt vmcnt(23)
	v_mov_b32_e32 v58, v64
	s_waitcnt vmcnt(22)
	v_mov_b32_e32 v59, v68
	v_mov_b32_e32 v68, v65
	v_mov_b32_e32 v64, v66
	v_mov_b32_e32 v65, v70
	v_mov_b32_e32 v70, v67
	s_waitcnt vmcnt(21)
; __device__ __forceinline__ unsigned pk2(float lo, float hi) { return pg8::cvt_pk_bf16(lo, hi); }
; __global__ void __launch_bounds__(NTHREADS, 2) fwd_megakernel(Params p) {
;     ...
;             for (int jj = 0; jj < 128; ++jj) { const float w = wo[(size_t)jj * 1024] * sc[jj];
; #pragma unroll
;                 for (int i = 0; i < 8; ++i) acc[i] += wp[i * 128 + jj] * w; }
;             u32x4 o; o.x = pk2(acc[0], acc[1]); o.y = pk2(acc[2], acc[3]); o.z = pk2(acc[4], acc[5]); o.w = pk2(acc[6], acc[7]);
;             *(u32x4*)((bf16_t*)(ws + WS_WOUT_E) + (size_t)e * 1024 * 1024 + (size_t)n * 1024 + 512 + g * 128 + k0) = o;
	v_mov_b32_e32 v66, v72
	s_waitcnt vmcnt(20)
	v_mov_b32_e32 v67, v76
	v_mov_b32_e32 v76, v73
	v_mov_b32_e32 v72, v74
	v_mov_b32_e32 v73, v78
	v_mov_b32_e32 v78, v75
	s_waitcnt vmcnt(19)
	v_mov_b32_e32 v74, v80
	s_waitcnt vmcnt(18)
	v_mov_b32_e32 v75, v84
	v_mov_b32_e32 v84, v81
	v_mov_b32_e32 v80, v82
	v_mov_b32_e32 v81, v86
	v_mov_b32_e32 v86, v83
	s_waitcnt vmcnt(17)
	v_mov_b32_e32 v82, v88
	s_waitcnt vmcnt(16)
	v_mov_b32_e32 v83, v92
	v_pk_fma_f32 v[12:13], v[160:161], v[36:37], v[12:13] op_sel_hi:[0,1,1]
	v_pk_fma_f32 v[10:11], v[160:161], v[46:47], v[10:11] op_sel_hi:[0,1,1]
	v_pk_fma_f32 v[8:9], v[160:161], v[54:55], v[8:9] op_sel_hi:[0,1,1]
	v_pk_fma_f32 v[6:7], v[160:161], v[62:63], v[6:7] op_sel_hi:[0,1,1]
	v_mul_f32_e32 v162, v163, v19
	v_mov_b32_e32 v92, v89
	v_pk_fma_f32 v[12:13], v[18:19], v[58:59], v[12:13] op_sel_hi:[0,1,1]
	v_pk_fma_f32 v[10:11], v[18:19], v[66:67], v[10:11] op_sel_hi:[0,1,1]
	v_pk_fma_f32 v[8:9], v[18:19], v[74:75], v[8:9] op_sel_hi:[0,1,1]
	v_pk_fma_f32 v[6:7], v[18:19], v[82:83], v[6:7] op_sel_hi:[0,1,1]
	v_mul_f32_e32 v20, v164, v20
	v_mov_b32_e32 v88, v90
	v_mov_b32_e32 v89, v94
	v_pk_fma_f32 v[12:13], v[162:163], v[68:69], v[12:13] op_sel_hi:[0,1,1]
	v_pk_fma_f32 v[10:11], v[162:163], v[76:77], v[10:11] op_sel_hi:[0,1,1]
	v_pk_fma_f32 v[8:9], v[162:163], v[84:85], v[8:9] op_sel_hi:[0,1,1]
	v_pk_fma_f32 v[6:7], v[162:163], v[92:93], v[6:7] op_sel_hi:[0,1,1]
	v_mul_f32_e32 v164, v165, v21
	v_mov_b32_e32 v94, v91
	v_pk_fma_f32 v[12:13], v[20:21], v[64:65], v[12:13] op_sel_hi:[0,1,1]
	v_pk_fma_f32 v[10:11], v[20:21], v[72:73], v[10:11] op_sel_hi:[0,1,1]
	v_pk_fma_f32 v[8:9], v[20:21], v[80:81], v[8:9] op_sel_hi:[0,1,1]
	v_pk_fma_f32 v[6:7], v[20:21], v[88:89], v[6:7] op_sel_hi:[0,1,1]
	v_mul_f32_e32 v22, v166, v22
	s_waitcnt vmcnt(15)
	v_mov_b32_e32 v90, v96
	s_waitcnt vmcnt(13)
	v_mov_b32_e32 v91, v104
	v_mov_b32_e32 v104, v97
	v_mov_b32_e32 v96, v98
	v_mov_b32_e32 v97, v106
	v_mov_b32_e32 v106, v99
	s_waitcnt vmcnt(11)
	v_mov_b32_e32 v98, v112
	s_waitcnt vmcnt(9)
	v_mov_b32_e32 v99, v120
	v_mov_b32_e32 v120, v113
	v_mov_b32_e32 v112, v114
	v_mov_b32_e32 v113, v122
	v_mov_b32_e32 v122, v115
	s_waitcnt vmcnt(7)
	v_mov_b32_e32 v114, v128
	s_waitcnt vmcnt(5)
	v_mov_b32_e32 v115, v136
	v_mov_b32_e32 v136, v129
	v_mov_b32_e32 v128, v130
	v_mov_b32_e32 v129, v138
	v_mov_b32_e32 v138, v131
	s_waitcnt vmcnt(3)
	v_mov_b32_e32 v130, v144
	s_waitcnt vmcnt(1)
	v_mov_b32_e32 v131, v152
	v_pk_fma_f32 v[12:13], v[164:165], v[70:71], v[12:13] op_sel_hi:[0,1,1]
	v_pk_fma_f32 v[10:11], v[164:165], v[78:79], v[10:11] op_sel_hi:[0,1,1]
	v_pk_fma_f32 v[8:9], v[164:165], v[86:87], v[8:9] op_sel_hi:[0,1,1]
	v_pk_fma_f32 v[6:7], v[164:165], v[94:95], v[6:7] op_sel_hi:[0,1,1]
	v_mul_f32_e32 v166, v167, v23
	v_mov_b32_e32 v152, v145
	v_pk_fma_f32 v[12:13], v[22:23], v[90:91], v[12:13] op_sel_hi:[0,1,1]
	v_pk_fma_f32 v[10:11], v[22:23], v[98:99], v[10:11] op_sel_hi:[0,1,1]
	v_pk_fma_f32 v[8:9], v[22:23], v[114:115], v[8:9] op_sel_hi:[0,1,1]
	v_pk_fma_f32 v[6:7], v[22:23], v[130:131], v[6:7] op_sel_hi:[0,1,1]
	v_mul_f32_e32 v24, v168, v24
	v_mov_b32_e32 v144, v146
	v_mov_b32_e32 v145, v154
	v_pk_fma_f32 v[12:13], v[166:167], v[104:105], v[12:13] op_sel_hi:[0,1,1]
	v_pk_fma_f32 v[10:11], v[166:167], v[120:121], v[10:11] op_sel_hi:[0,1,1]
	v_pk_fma_f32 v[8:9], v[166:167], v[136:137], v[8:9] op_sel_hi:[0,1,1]
	v_pk_fma_f32 v[6:7], v[166:167], v[152:153], v[6:7] op_sel_hi:[0,1,1]
	v_mul_f32_e32 v168, v169, v25
	v_mov_b32_e32 v154, v147
	v_pk_fma_f32 v[12:13], v[24:25], v[96:97], v[12:13] op_sel_hi:[0,1,1]
	v_pk_fma_f32 v[10:11], v[24:25], v[112:113], v[10:11] op_sel_hi:[0,1,1]
	v_pk_fma_f32 v[8:9], v[24:25], v[128:129], v[8:9] op_sel_hi:[0,1,1]
	v_pk_fma_f32 v[6:7], v[24:25], v[144:145], v[6:7] op_sel_hi:[0,1,1]
	v_mul_f32_e32 v26, v170, v26
	v_mov_b32_e32 v146, v100
	v_mov_b32_e32 v147, v108
	v_mov_b32_e32 v108, v101
	v_mov_b32_e32 v100, v102
	v_mov_b32_e32 v101, v110
	v_mov_b32_e32 v110, v103
	v_mov_b32_e32 v102, v116
	v_mov_b32_e32 v103, v124
	v_mov_b32_e32 v124, v117
	v_mov_b32_e32 v116, v118
	v_mov_b32_e32 v117, v126
	v_mov_b32_e32 v126, v119
	v_mov_b32_e32 v118, v132
	v_mov_b32_e32 v119, v140
	v_mov_b32_e32 v140, v133
	v_mov_b32_e32 v132, v134
	v_mov_b32_e32 v133, v142
	v_mov_b32_e32 v142, v135
	v_mov_b32_e32 v134, v148
	s_waitcnt vmcnt(0)
	v_mov_b32_e32 v135, v156
	v_pk_fma_f32 v[12:13], v[168:169], v[106:107], v[12:13] op_sel_hi:[0,1,1]
	v_pk_fma_f32 v[10:11], v[168:169], v[122:123], v[10:11] op_sel_hi:[0,1,1]
	v_pk_fma_f32 v[8:9], v[168:169], v[138:139], v[8:9] op_sel_hi:[0,1,1]
	v_pk_fma_f32 v[6:7], v[168:169], v[154:155], v[6:7] op_sel_hi:[0,1,1]
	v_mul_f32_e32 v170, v173, v27
	v_mov_b32_e32 v156, v149
	v_pk_fma_f32 v[12:13], v[26:27], v[146:147], v[12:13] op_sel_hi:[0,1,1]
	v_pk_fma_f32 v[10:11], v[26:27], v[102:103], v[10:11] op_sel_hi:[0,1,1]
	v_pk_fma_f32 v[8:9], v[26:27], v[118:119], v[8:9] op_sel_hi:[0,1,1]
	v_pk_fma_f32 v[6:7], v[26:27], v[134:135], v[6:7] op_sel_hi:[0,1,1]
	v_mul_f32_e32 v28, v171, v28
	v_mov_b32_e32 v148, v150
	v_mov_b32_e32 v149, v158
	v_pk_fma_f32 v[12:13], v[170:171], v[108:109], v[12:13] op_sel_hi:[0,1,1]
	v_pk_fma_f32 v[10:11], v[170:171], v[124:125], v[10:11] op_sel_hi:[0,1,1]
	v_pk_fma_f32 v[8:9], v[170:171], v[140:141], v[8:9] op_sel_hi:[0,1,1]
	v_pk_fma_f32 v[6:7], v[170:171], v[156:157], v[6:7] op_sel_hi:[0,1,1]
	v_mul_f32_e32 v172, v172, v29
	v_mov_b32_e32 v158, v151
	v_pk_fma_f32 v[12:13], v[28:29], v[100:101], v[12:13] op_sel_hi:[0,1,1]
	v_pk_fma_f32 v[10:11], v[28:29], v[116:117], v[10:11] op_sel_hi:[0,1,1]
	v_pk_fma_f32 v[8:9], v[28:29], v[132:133], v[8:9] op_sel_hi:[0,1,1]
	v_pk_fma_f32 v[6:7], v[28:29], v[148:149], v[6:7] op_sel_hi:[0,1,1]
	v_pk_fma_f32 v[12:13], v[172:173], v[110:111], v[12:13] op_sel_hi:[0,1,1]
	v_pk_fma_f32 v[10:11], v[172:173], v[126:127], v[10:11] op_sel_hi:[0,1,1]
	v_pk_fma_f32 v[8:9], v[172:173], v[142:143], v[8:9] op_sel_hi:[0,1,1]
	v_pk_fma_f32 v[6:7], v[172:173], v[158:159], v[6:7] op_sel_hi:[0,1,1]
	s_cbranch_scc0 .LBB0_15
	s_lshl_b32 s0, s44, 6
	s_and_b32 s0, s0, 0x3c0
	s_and_b32 s16, s16, 3
	v_or_b32_e32 v2, s0, v1
	s_lshl_b64 s[0:1], s[20:21], 21
	s_add_u32 s0, s68, s0
	s_addc_u32 s1, s69, s1
	v_lshlrev_b32_e32 v2, 11, v2
	v_lshl_add_u64 v[4:5], s[0:1], 0, v[2:3]
	s_lshl_b32 s16, s16, 8
	v_lshl_add_u64 v[4:5], v[4:5], 0, s[16:17]
	s_and_b32 s16, s44, 0xf0
	v_lshl_add_u64 v[4:5], v[4:5], 0, s[16:17]
	v_add_co_u32_e32 v4, vcc, 0x500000, v4
	s_add_i32 s44, s44, s88
	s_add_i32 s29, s29, s38
	v_addc_co_u32_e32 v5, vcc, 0, v5, vcc
	s_cmpk_gt_i32 s44, 0x7ff
	v_cvt_pk_bf16_f32 v12, v12, v13
	v_cvt_pk_bf16_f32 v13, v10, v11
	v_cvt_pk_bf16_f32 v14, v8, v9
	v_cvt_pk_bf16_f32 v15, v6, v7
	global_store_dwordx4 v[4:5], v[12:15], off offset:1024
	s_cbranch_scc0 .LBB0_14

; __global__ void __launch_bounds__(NTHREADS, 2) fwd_megakernel(Params p) {
;     ...
;     for (int r0 = gw_f * 4; r0 < NTOK; r0 += NGW * 4) {
;         unsigned long long xw[4][4];
;         float ps = PART[(size_t)(lane_f & 15) * NTOK + r0 + (lane_f >> 4)];
; #pragma unroll
;         for (int q = 0; q < 4; ++q) { const unsigned long long* xr = (const unsigned long long*)(XB + (size_t)(r0 + q) * DM) + lane_f;
; #pragma unroll
;             for (int jj = 0; jj < 4; ++jj) xw[q][jj] = xr[64 * jj]; }
;         ps += __builtin_bit_cast(float, __builtin_amdgcn_mov_dpp(__builtin_bit_cast(int, ps), 0xB1, 0xF, 0xF, true));
;         ps += __builtin_bit_cast(float, __builtin_amdgcn_mov_dpp(__builtin_bit_cast(int, ps), 0x4E, 0xF, 0xF, true));
;         ps += __builtin_bit_cast(float, __builtin_amdgcn_mov_dpp(__builtin_bit_cast(int, ps), 0x124, 0xF, 0xF, true));
;         ps += __builtin_bit_cast(float, __builtin_amdgcn_mov_dpp(__builtin_bit_cast(int, ps), 0x128, 0xF, 0xF, true));
;         const f32x4* gr = (const f32x4*)p.norm_final + lane_f;
; #pragma unroll
;         for (int q = 0; q < 4; ++q) {
;             const float s = __builtin_bit_cast(float, __builtin_amdgcn_readlane(__builtin_bit_cast(int, ps), 16 * q));
;             const float rs = __builtin_amdgcn_rsqf(s * (1.0f / 1024.0f) + 1e-6f);
;             f32x4* orow = (f32x4*)(p.out + (size_t)(r0 + q) * DM) + lane_f;
; #pragma unroll
;             for (int jj = 0; jj < 4; ++jj) { const unsigned long long w = xw[q][jj]; const unsigned lo = (unsigned)w, hi = (unsigned)(w >> 32); const f32x4 gg = gr[64 * jj];
;                 f32x4 v; v[0] = __uint_as_float(lo << 16); v[1] = __uint_as_float(lo & 0xffff0000u); v[2] = __uint_as_float(hi << 16); v[3] = __uint_as_float(hi & 0xffff0000u);
;                 __builtin_nontemporal_store(v * rs * gg, &orow[64 * jj]); }
;         }
.LBB0_999:
	v_lshl_add_u64 v[8:9], s[68:69], 0, v[6:7]
	global_load_dword v52, v[8:9], off
	v_lshl_add_u64 v[10:11], s[68:69], 0, v[4:5]
	v_add_co_u32_e32 v24, vcc, 0x6000000, v10
	s_add_i32 s64, s64, s16
	s_nop 0
	v_addc_co_u32_e32 v25, vcc, 0, v11, vcc
	global_load_dwordx2 v[26:27], v[24:25], off nt
	global_load_dwordx4 v[20:23], v[0:1], off
	v_add_co_u32_e32 v28, vcc, s7, v2
	global_load_dwordx2 v[32:33], v[24:25], off offset:512 nt
	global_load_dwordx2 v[34:35], v[24:25], off offset:1024 nt
	global_load_dwordx2 v[36:37], v[24:25], off offset:1536 nt
	global_load_dwordx2 v[38:39], v[24:25], off offset:2048 nt
	global_load_dwordx2 v[40:41], v[24:25], off offset:2560 nt
	global_load_dwordx2 v[42:43], v[24:25], off offset:3072 nt
	v_addc_co_u32_e32 v29, vcc, -1, v3, vcc
	v_add_co_u32_e32 v30, vcc, s6, v10
	v_lshl_add_u64 v[4:5], v[4:5], 0, s[2:3]
	s_nop 0
	v_addc_co_u32_e32 v31, vcc, 0, v11, vcc
	global_load_dwordx2 v[44:45], v[24:25], off offset:3584 nt
	global_load_dwordx2 v[46:47], v[30:31], off nt
	global_load_dwordx2 v[48:49], v[30:31], off offset:512 nt
	global_load_dwordx2 v[50:51], v[30:31], off offset:1024 nt
	global_load_dwordx2 v[16:17], v[30:31], off offset:1536 nt
	global_load_dwordx2 v[14:15], v[30:31], off offset:2048 nt
	global_load_dwordx2 v[12:13], v[30:31], off offset:2560 nt
	global_load_dwordx2 v[10:11], v[30:31], off offset:3072 nt
	global_load_dwordx2 v[8:9], v[30:31], off offset:3584 nt
	v_lshl_add_u64 v[6:7], v[6:7], 0, s[4:5]
	s_cmp_gt_i32 s64, 0xffff
	s_waitcnt vmcnt(17)
	v_add_f32_dpp v24, v52, v52 quad_perm:[1,0,3,2] row_mask:0xf bank_mask:0xf bound_ctrl:1
	s_nop 1
	v_add_f32_dpp v24, v24, v24 quad_perm:[2,3,0,1] row_mask:0xf bank_mask:0xf bound_ctrl:1
	s_waitcnt vmcnt(16)
	v_and_b32_e32 v25, 0xffff0000, v26
	v_add_f32_dpp v30, v24, v24 row_ror:4 row_mask:0xf bank_mask:0xf bound_ctrl:1
	v_lshlrev_b32_e32 v24, 16, v26
	v_lshlrev_b32_e32 v26, 16, v27
	v_add_f32_dpp v31, v30, v30 row_ror:8 row_mask:0xf bank_mask:0xf bound_ctrl:1
	v_and_b32_e32 v27, 0xffff0000, v27
	v_readlane_b32 s10, v31, 0
	s_nop 1
	v_fma_f32 v30, s10, v19, v18
	v_rsq_f32_e32 v30, v30
	v_readlane_b32 s10, v31, 16
	v_pk_mul_f32 v[24:25], v[30:31], v[24:25] op_sel_hi:[0,1]
	v_pk_mul_f32 v[26:27], v[30:31], v[26:27] op_sel_hi:[0,1]
	s_waitcnt vmcnt(15)
	v_pk_mul_f32 v[22:23], v[22:23], v[26:27]
	v_pk_mul_f32 v[20:21], v[20:21], v[24:25]
	global_store_dwordx4 v[28:29], v[20:23], off offset:-3072 nt
	global_load_dwordx4 v[20:23], v[0:1], off offset:1024
	s_waitcnt vmcnt(16)
	v_lshlrev_b32_e32 v24, 16, v32
	v_and_b32_e32 v25, 0xffff0000, v32
	v_lshlrev_b32_e32 v26, 16, v33
	v_and_b32_e32 v27, 0xffff0000, v33
	v_pk_mul_f32 v[26:27], v[30:31], v[26:27] op_sel_hi:[0,1]
	v_pk_mul_f32 v[24:25], v[30:31], v[24:25] op_sel_hi:[0,1]
	s_waitcnt vmcnt(0)
	v_pk_mul_f32 v[20:21], v[20:21], v[24:25]
	v_pk_mul_f32 v[22:23], v[22:23], v[26:27]
	global_store_dwordx4 v[28:29], v[20:23], off offset:-2048 nt
	global_load_dwordx4 v[20:23], v[0:1], off offset:2048
	v_lshlrev_b32_e32 v24, 16, v34
	v_and_b32_e32 v25, 0xffff0000, v34
	v_lshlrev_b32_e32 v26, 16, v35
	v_and_b32_e32 v27, 0xffff0000, v35
	v_pk_mul_f32 v[26:27], v[30:31], v[26:27] op_sel_hi:[0,1]
	v_pk_mul_f32 v[24:25], v[30:31], v[24:25] op_sel_hi:[0,1]
	s_waitcnt vmcnt(0)
	v_pk_mul_f32 v[20:21], v[20:21], v[24:25]
	v_pk_mul_f32 v[22:23], v[22:23], v[26:27]
	global_store_dwordx4 v[28:29], v[20:23], off offset:-1024 nt
	global_load_dwordx4 v[20:23], v[0:1], off offset:3072
	v_lshlrev_b32_e32 v26, 16, v36
	v_and_b32_e32 v27, 0xffff0000, v36
	v_lshlrev_b32_e32 v28, 16, v37
	v_and_b32_e32 v29, 0xffff0000, v37
	v_add_co_u32_e32 v24, vcc, s8, v2
	v_pk_mul_f32 v[28:29], v[30:31], v[28:29] op_sel_hi:[0,1]
	v_pk_mul_f32 v[26:27], v[30:31], v[26:27] op_sel_hi:[0,1]
	v_addc_co_u32_e32 v25, vcc, -1, v3, vcc
	v_fma_f32 v30, s10, v19, v18
	v_rsq_f32_e32 v30, v30
	v_readlane_b32 s10, v31, 32
	s_waitcnt vmcnt(0)
	v_pk_mul_f32 v[20:21], v[20:21], v[26:27]
	v_pk_mul_f32 v[22:23], v[22:23], v[28:29]
	global_store_dwordx4 v[24:25], v[20:23], off offset:-4096 nt
	global_load_dwordx4 v[20:23], v[0:1], off
	v_lshlrev_b32_e32 v26, 16, v38
	v_and_b32_e32 v27, 0xffff0000, v38
	v_lshlrev_b32_e32 v28, 16, v39
	v_and_b32_e32 v29, 0xffff0000, v39
	v_pk_mul_f32 v[28:29], v[30:31], v[28:29] op_sel_hi:[0,1]
	v_pk_mul_f32 v[26:27], v[30:31], v[26:27] op_sel_hi:[0,1]
	s_waitcnt vmcnt(0)
	v_pk_mul_f32 v[20:21], v[20:21], v[26:27]
	v_pk_mul_f32 v[22:23], v[22:23], v[28:29]
	global_store_dwordx4 v[24:25], v[20:23], off offset:-3072 nt
	global_load_dwordx4 v[20:23], v[0:1], off offset:1024
	v_lshlrev_b32_e32 v26, 16, v40
	v_and_b32_e32 v27, 0xffff0000, v40
	v_lshlrev_b32_e32 v28, 16, v41
	v_and_b32_e32 v29, 0xffff0000, v41
	v_pk_mul_f32 v[28:29], v[30:31], v[28:29] op_sel_hi:[0,1]
	v_pk_mul_f32 v[26:27], v[30:31], v[26:27] op_sel_hi:[0,1]
	s_waitcnt vmcnt(0)
; __global__ void __launch_bounds__(NTHREADS, 2) fwd_megakernel(Params p) {
;     ...
;         for (int q = 0; q < 4; ++q) {
;             const float s = __builtin_bit_cast(float, __builtin_amdgcn_readlane(__builtin_bit_cast(int, ps), 16 * q));
;             const float rs = __builtin_amdgcn_rsqf(s * (1.0f / 1024.0f) + 1e-6f);
;             f32x4* orow = (f32x4*)(p.out + (size_t)(r0 + q) * DM) + lane_f;
; #pragma unroll
;             for (int jj = 0; jj < 4; ++jj) { const unsigned long long w = xw[q][jj]; const unsigned lo = (unsigned)w, hi = (unsigned)(w >> 32); const f32x4 gg = gr[64 * jj];
;                 f32x4 v; v[0] = __uint_as_float(lo << 16); v[1] = __uint_as_float(lo & 0xffff0000u); v[2] = __uint_as_float(hi << 16); v[3] = __uint_as_float(hi & 0xffff0000u);
;                 __builtin_nontemporal_store(v * rs * gg, &orow[64 * jj]); }
;         }
	v_pk_mul_f32 v[20:21], v[20:21], v[26:27]
	v_pk_mul_f32 v[22:23], v[22:23], v[28:29]
	global_store_dwordx4 v[24:25], v[20:23], off offset:-2048 nt
	global_load_dwordx4 v[20:23], v[0:1], off offset:2048
	v_lshlrev_b32_e32 v26, 16, v42
	v_and_b32_e32 v27, 0xffff0000, v42
	v_lshlrev_b32_e32 v28, 16, v43
	v_and_b32_e32 v29, 0xffff0000, v43
	v_pk_mul_f32 v[28:29], v[30:31], v[28:29] op_sel_hi:[0,1]
	v_pk_mul_f32 v[26:27], v[30:31], v[26:27] op_sel_hi:[0,1]
	s_waitcnt vmcnt(0)
	v_pk_mul_f32 v[20:21], v[20:21], v[26:27]
	v_pk_mul_f32 v[22:23], v[22:23], v[28:29]
	global_store_dwordx4 v[24:25], v[20:23], off offset:-1024 nt
	global_load_dwordx4 v[20:23], v[0:1], off offset:3072
	v_lshlrev_b32_e32 v26, 16, v44
	v_and_b32_e32 v27, 0xffff0000, v44
	v_lshlrev_b32_e32 v28, 16, v45
	v_and_b32_e32 v29, 0xffff0000, v45
	v_pk_mul_f32 v[28:29], v[30:31], v[28:29] op_sel_hi:[0,1]
	v_pk_mul_f32 v[26:27], v[30:31], v[26:27] op_sel_hi:[0,1]
	v_fma_f32 v30, s10, v19, v18
	v_rsq_f32_e32 v30, v30
	v_readlane_b32 s10, v31, 48
	s_waitcnt vmcnt(0)
	v_pk_mul_f32 v[20:21], v[20:21], v[26:27]
	v_pk_mul_f32 v[22:23], v[22:23], v[28:29]
	global_store_dwordx4 v[24:25], v[20:23], off nt
	global_load_dwordx4 v[20:23], v[0:1], off
	v_lshlrev_b32_e32 v26, 16, v46
	v_and_b32_e32 v27, 0xffff0000, v46
	v_lshlrev_b32_e32 v28, 16, v47
	v_and_b32_e32 v29, 0xffff0000, v47
	v_add_co_u32_e32 v24, vcc, s9, v2
	v_pk_mul_f32 v[28:29], v[30:31], v[28:29] op_sel_hi:[0,1]
	v_pk_mul_f32 v[26:27], v[30:31], v[26:27] op_sel_hi:[0,1]
	v_addc_co_u32_e32 v25, vcc, -1, v3, vcc
	s_waitcnt vmcnt(0)
	v_pk_mul_f32 v[20:21], v[20:21], v[26:27]
	v_pk_mul_f32 v[22:23], v[22:23], v[28:29]
	global_store_dwordx4 v[24:25], v[20:23], off offset:-3072 nt
	global_load_dwordx4 v[20:23], v[0:1], off offset:1024
	v_lshlrev_b32_e32 v26, 16, v48
	v_and_b32_e32 v27, 0xffff0000, v48
	v_lshlrev_b32_e32 v28, 16, v49
	v_and_b32_e32 v29, 0xffff0000, v49
	v_pk_mul_f32 v[28:29], v[30:31], v[28:29] op_sel_hi:[0,1]
	v_pk_mul_f32 v[26:27], v[30:31], v[26:27] op_sel_hi:[0,1]
	s_waitcnt vmcnt(0)
	v_pk_mul_f32 v[20:21], v[20:21], v[26:27]
	v_pk_mul_f32 v[22:23], v[22:23], v[28:29]
	global_store_dwordx4 v[24:25], v[20:23], off offset:-2048 nt
	global_load_dwordx4 v[20:23], v[0:1], off offset:2048
	v_lshlrev_b32_e32 v26, 16, v50
	v_and_b32_e32 v27, 0xffff0000, v50
	v_lshlrev_b32_e32 v28, 16, v51
	v_and_b32_e32 v29, 0xffff0000, v51
	v_pk_mul_f32 v[28:29], v[30:31], v[28:29] op_sel_hi:[0,1]
	v_pk_mul_f32 v[26:27], v[30:31], v[26:27] op_sel_hi:[0,1]
	s_waitcnt vmcnt(0)
	v_pk_mul_f32 v[20:21], v[20:21], v[26:27]
	v_pk_mul_f32 v[22:23], v[22:23], v[28:29]
	global_store_dwordx4 v[24:25], v[20:23], off offset:-1024 nt
	global_load_dwordx4 v[20:23], v[0:1], off offset:3072
	v_lshlrev_b32_e32 v24, 16, v16
	v_and_b32_e32 v25, 0xffff0000, v16
	v_lshlrev_b32_e32 v16, 16, v17
	v_and_b32_e32 v17, 0xffff0000, v17
	v_pk_mul_f32 v[16:17], v[30:31], v[16:17] op_sel_hi:[0,1]
	v_pk_mul_f32 v[24:25], v[30:31], v[24:25] op_sel_hi:[0,1]
	s_waitcnt vmcnt(0)
	v_pk_mul_f32 v[20:21], v[20:21], v[24:25]
	v_pk_mul_f32 v[22:23], v[22:23], v[16:17]
	global_store_dwordx4 v[2:3], v[20:23], off offset:-4096 nt
	global_load_dwordx4 v[20:23], v[0:1], off
	v_fma_f32 v24, s10, v19, v18
	v_rsq_f32_e32 v24, v24
	v_lshlrev_b32_e32 v16, 16, v14
	v_and_b32_e32 v17, 0xffff0000, v14
	v_lshlrev_b32_e32 v14, 16, v15
	v_and_b32_e32 v15, 0xffff0000, v15
	v_pk_mul_f32 v[26:27], v[24:25], v[14:15] op_sel_hi:[0,1]
	v_pk_mul_f32 v[14:15], v[24:25], v[16:17] op_sel_hi:[0,1]
	s_waitcnt vmcnt(0)
	v_pk_mul_f32 v[14:15], v[20:21], v[14:15]
	v_pk_mul_f32 v[16:17], v[22:23], v[26:27]
	global_store_dwordx4 v[2:3], v[14:17], off offset:-3072 nt
	global_load_dwordx4 v[14:17], v[0:1], off offset:1024
	v_lshlrev_b32_e32 v20, 16, v12
	v_and_b32_e32 v21, 0xffff0000, v12
	v_lshlrev_b32_e32 v12, 16, v13
	v_and_b32_e32 v13, 0xffff0000, v13
	v_pk_mul_f32 v[22:23], v[24:25], v[12:13] op_sel_hi:[0,1]
	v_pk_mul_f32 v[12:13], v[24:25], v[20:21] op_sel_hi:[0,1]
	s_waitcnt vmcnt(0)
	v_pk_mul_f32 v[12:13], v[14:15], v[12:13]
	v_pk_mul_f32 v[14:15], v[16:17], v[22:23]
	global_store_dwordx4 v[2:3], v[12:15], off offset:-2048 nt
	global_load_dwordx4 v[12:15], v[0:1], off offset:2048
	v_lshlrev_b32_e32 v16, 16, v10
	v_and_b32_e32 v17, 0xffff0000, v10
	v_lshlrev_b32_e32 v10, 16, v11
	v_and_b32_e32 v11, 0xffff0000, v11
	v_pk_mul_f32 v[20:21], v[24:25], v[10:11] op_sel_hi:[0,1]
	v_pk_mul_f32 v[10:11], v[24:25], v[16:17] op_sel_hi:[0,1]
	s_waitcnt vmcnt(0)
	v_pk_mul_f32 v[10:11], v[12:13], v[10:11]
	v_pk_mul_f32 v[12:13], v[14:15], v[20:21]
	global_store_dwordx4 v[2:3], v[10:13], off offset:-1024 nt
	global_load_dwordx4 v[10:13], v[0:1], off offset:3072
	v_lshlrev_b32_e32 v14, 16, v8
	v_and_b32_e32 v15, 0xffff0000, v8
	v_lshlrev_b32_e32 v8, 16, v9
	v_and_b32_e32 v9, 0xffff0000, v9
	v_pk_mul_f32 v[16:17], v[24:25], v[8:9] op_sel_hi:[0,1]
	v_pk_mul_f32 v[8:9], v[24:25], v[14:15] op_sel_hi:[0,1]
	s_waitcnt vmcnt(0)
	v_pk_mul_f32 v[8:9], v[10:11], v[8:9]
	v_pk_mul_f32 v[10:11], v[12:13], v[16:17]
	global_store_dwordx4 v[2:3], v[8:11], off nt
	v_lshl_add_u64 v[2:3], v[2:3], 0, s[0:1]
	s_cbranch_scc0 .LBB0_999
